# static priority (flips deleted) + P1 permlane row-sum reductions + P1 unit balance + pooling fast path
# speedup vs baseline: 1.0004x; 1.0004x over previous
;     __host__ __device__ bool next(int i, Unit& u) const { return i < cnt ? so.next(base + i, u) : false; }
;     __host__ __device__ bool next(int i, Unit& u) const { const int L = i * G + c; if (L >= 32) return false; u.g = L >> 3; u.pm = L & 7; u.pn = 0; return true; }
; #define PG8_WAIT_V(n) asm volatile("s_waitcnt vmcnt(" #n ")" ::: "memory")
; #define PG8_BAR __builtin_amdgcn_s_barrier()
; template <class Epi, class Sched, bool ALIGN_EPI = false, bool SP2 = false>
; __device__ __forceinline__ void gemm_phase(PG8_LAS unsigned char* lds, const Gemm g, const Sched& S, const Epi& E) {
;     ...
; #pragma unroll
;     for (int a = 0; a < 2; ++a)
; #pragma unroll
;         for (int b = 0; b < 2; ++b)
; #pragma unroll
;             for (int m = 0; m < 4; ++m)
; #pragma unroll
;                 for (int n = 0; n < 2; ++n) acc[a][b][m][n] = (f32x4){0.f, 0.f, 0.f, 0.f};
;     bf16x8 At[4][2], B0[2][2], B1[2][2];
;     const char* cA = (const char*)(g.A + (size_t)cur.g * g.gsA) + (size_t)cur.pm * tstepA; const char* cB = (const char*)(g.Bt + (size_t)cur.g * g.gsB) + (size_t)cur.pn * tstepB;
;     S.a_ready(cur);
;     if constexpr (SP2) {
;         PG8_STAGE(PG8_SB(0, 0), cB, voffB); PG8_STAGE(PG8_SB(0, 1), cB + hstepB, voffB); PG8_STAGE(PG8_SA(0, 0), cA, voffA); PG8_STAGE(PG8_SA(0, 1), cA + hstepA, voffA);
;         if (wr == 1) PG8_BAR;
;         PG8_WAIT_V(2); PG8_BAR;
;         PG8_STAGE(PG8_SB(1, 0), cB + kstep, voffB); PG8_STAGE(PG8_SA(1, 0), cA + kstep, voffA); PG8_STAGE(PG8_SB(1, 1), cB + hstepB + kstep, voffB);
;         PG8_WAIT_V(6); PG8_BAR;
;     } else {
;         PG8_STAGE(PG8_SB(0, 0), cB, voffB); PG8_STAGE(PG8_SA(0, 0), cA, voffA); PG8_STAGE(PG8_SB(0, 1), cB + hstepB, voffB); PG8_STAGE(PG8_SA(0, 1), cA + hstepA, voffA);
;         if (wr == 1) PG8_BAR;
;         PG8_WAIT_V(4); PG8_BAR;
;         PG8_STAGE(PG8_SB(1, 0), cB + kstep, voffB); PG8_STAGE(PG8_SA(1, 0), cA + kstep, voffA); PG8_STAGE(PG8_SB(1, 1), cB + hstepB + kstep, voffB);
;         PG8_WAIT_V(6); PG8_BAR;
;     }
;     for (;;) {
;         const bool has_next = S.next(ui + 1, nxt);
;         const char* nA = has_next ? (const char*)(g.A + (size_t)nxt.g * g.gsA) + (size_t)nxt.pm * tstepA : cA; const char* nB = has_next ? (const char*)(g.Bt + (size_t)nxt.g * g.gsB) + (size_t)nxt.pn * tstepB : cB;
;         for (int t = 0; t < nt; t += 2) {
.LBB0_84:
	s_lshl_b32 s32, s63, 4
	s_and_b32 s32, s32, 16
	s_xor_b32 s22, s22, s32
	s_ashr_i32 s25, s24, 31
	s_lshl_b64 s[26:27], s[24:25], 20
	s_add_u32 s26, s37, s26
	s_addc_u32 s27, s38, s27
	s_ashr_i32 s23, s22, 31
	s_lshl_b64 s[28:29], s[22:23], 20
	s_add_u32 s28, s39, s28
	v_mov_b32_e32 v127, 0
	s_addc_u32 s29, s44, s29
	s_and_b64 vcc, exec, s[6:7]
	v_mov_b32_e32 v126, v127
	v_mov_b32_e32 v125, v127
	v_mov_b32_e32 v124, v127
	v_mov_b32_e32 v123, v127
	v_mov_b32_e32 v122, v127
	v_mov_b32_e32 v121, v127
	v_mov_b32_e32 v120, v127
	v_mov_b32_e32 v111, v127
	v_mov_b32_e32 v110, v127
	v_mov_b32_e32 v109, v127
	v_mov_b32_e32 v108, v127
	v_mov_b32_e32 v107, v127
	v_mov_b32_e32 v106, v127
	v_mov_b32_e32 v105, v127
	v_mov_b32_e32 v104, v127
	v_mov_b32_e32 v95, v127
	v_mov_b32_e32 v94, v127
	v_mov_b32_e32 v93, v127
	v_mov_b32_e32 v92, v127
	v_mov_b32_e32 v91, v127
	v_mov_b32_e32 v90, v127
	v_mov_b32_e32 v89, v127
	v_mov_b32_e32 v88, v127
	v_mov_b32_e32 v79, v127
	v_mov_b32_e32 v78, v127
	v_mov_b32_e32 v77, v127
	v_mov_b32_e32 v76, v127
	v_mov_b32_e32 v75, v127
	v_mov_b32_e32 v74, v127
	v_mov_b32_e32 v73, v127
	v_mov_b32_e32 v72, v127
	v_mov_b32_e32 v119, v127
	v_mov_b32_e32 v118, v127
	v_mov_b32_e32 v117, v127
	v_mov_b32_e32 v116, v127
	v_mov_b32_e32 v115, v127
	v_mov_b32_e32 v114, v127
	v_mov_b32_e32 v113, v127
	v_mov_b32_e32 v112, v127
	v_mov_b32_e32 v103, v127
	v_mov_b32_e32 v102, v127
	v_mov_b32_e32 v101, v127
	v_mov_b32_e32 v100, v127
	v_mov_b32_e32 v99, v127
	v_mov_b32_e32 v98, v127
	v_mov_b32_e32 v97, v127
	v_mov_b32_e32 v96, v127
	v_mov_b32_e32 v87, v127
	v_mov_b32_e32 v86, v127
	v_mov_b32_e32 v85, v127
	v_mov_b32_e32 v84, v127
	v_mov_b32_e32 v83, v127
	v_mov_b32_e32 v82, v127
	v_mov_b32_e32 v81, v127
	v_mov_b32_e32 v80, v127
	v_mov_b32_e32 v71, v127
	v_mov_b32_e32 v70, v127
	v_mov_b32_e32 v69, v127
	v_mov_b32_e32 v68, v127
	v_mov_b32_e32 v67, v127
	v_mov_b32_e32 v66, v127
	v_mov_b32_e32 v65, v127
	v_mov_b32_e32 v64, v127
	v_mov_b32_e32 v63, v127
	v_mov_b32_e32 v62, v127
	v_mov_b32_e32 v61, v127
	v_mov_b32_e32 v60, v127
	v_mov_b32_e32 v59, v127
	v_mov_b32_e32 v58, v127
	v_mov_b32_e32 v57, v127
	v_mov_b32_e32 v56, v127
	v_mov_b32_e32 v47, v127
	v_mov_b32_e32 v46, v127
	v_mov_b32_e32 v45, v127
	v_mov_b32_e32 v44, v127
	v_mov_b32_e32 v43, v127
	v_mov_b32_e32 v42, v127
	v_mov_b32_e32 v41, v127
	v_mov_b32_e32 v40, v127
	v_mov_b32_e32 v31, v127
	v_mov_b32_e32 v30, v127
	v_mov_b32_e32 v29, v127
	v_mov_b32_e32 v28, v127
	v_mov_b32_e32 v27, v127
	v_mov_b32_e32 v26, v127
	v_mov_b32_e32 v25, v127
	v_mov_b32_e32 v24, v127
	v_mov_b32_e32 v15, v127
	v_mov_b32_e32 v14, v127
	v_mov_b32_e32 v13, v127
	v_mov_b32_e32 v12, v127
	v_mov_b32_e32 v11, v127
	v_mov_b32_e32 v10, v127
	v_mov_b32_e32 v9, v127
	v_mov_b32_e32 v8, v127
	v_mov_b32_e32 v55, v127
	v_mov_b32_e32 v54, v127
	v_mov_b32_e32 v53, v127
	v_mov_b32_e32 v52, v127
	v_mov_b32_e32 v51, v127
	v_mov_b32_e32 v50, v127
	v_mov_b32_e32 v49, v127
	v_mov_b32_e32 v48, v127
	v_mov_b32_e32 v39, v127
	v_mov_b32_e32 v38, v127
	v_mov_b32_e32 v37, v127
	v_mov_b32_e32 v36, v127
	v_mov_b32_e32 v35, v127
	v_mov_b32_e32 v34, v127
	v_mov_b32_e32 v33, v127
	v_mov_b32_e32 v32, v127
	v_mov_b32_e32 v23, v127
	v_mov_b32_e32 v22, v127
	v_mov_b32_e32 v21, v127
	v_mov_b32_e32 v20, v127
	v_mov_b32_e32 v19, v127
	v_mov_b32_e32 v18, v127
	v_mov_b32_e32 v17, v127
	v_mov_b32_e32 v16, v127
	v_mov_b32_e32 v7, v127
	v_mov_b32_e32 v6, v127
	v_mov_b32_e32 v5, v127
	v_mov_b32_e32 v4, v127
	v_mov_b32_e32 v3, v127
	v_mov_b32_e32 v2, v127
	s_waitcnt lgkmcnt(0)
	v_mov_b32_e32 v1, v127
	v_mov_b32_e32 v0, v127
	s_cbranch_vccnz .LBB0_87
	s_and_b64 s[34:35], s[8:9], exec
	s_cselect_b32 s11, s27, s31
	s_cselect_b32 s23, s26, s30
	s_cselect_b32 s25, s29, s13
	s_cselect_b32 s40, s28, s12
	s_add_u32 s41, s12, 0x100
	s_addc_u32 s42, s13, 0
	s_add_u32 s12, s30, 0x80080
	s_addc_u32 s13, s31, 0
	s_mov_b32 s30, 0
	v_readfirstlane_b32 s32, v227
	s_nop 3
	s_lshr_b32 s32, s32, 6
	s_cmp_ge_u32 s32, 4
	s_cbranch_scc0 .Lprio_0
	s_setprio 1
